# stacked: phase-0 conversion loads hoisted + phase-1 row prefetch + barrier tail polling TOP + in-proj map v3
# speedup vs baseline: 1.0072x; 1.0055x over previous
; __device__ void phase0(LAS unsigned char* lds, const Params& p, int it_lo, int it_hi) {
;     ...
;     for (int it = it_lo + blockIdx.x; it < it_hi; it += gridDim.x) {
;         if (it < 192) {
;             const int cc = it % 48, kq = it / 48;
;             LAS float* sil = fl; LAS float* red = fl + 2304;
;             for (int i = tid; i < 2304; i += NTHR) { const int j = i >> 8, k = kq * 256 + (i & 255); const float v = (j < 8) ? p.c[j * 1024 + k] : p.c_ctx[k]; sil[i] = siluf_(v); }
;             __syncthreads();
;             const int n = tid & 63, ks = tid >> 6;
;             const float* wp = p.w_mod + (size_t)(kq * 256 + ks * 32) * 3072 + cc * 64 + n;
;             float a[9];
; #pragma unroll
;             for (int j = 0; j < 9; ++j) a[j] = 0.f;
; #pragma unroll 8
;             for (int kk = 0; kk < 32; ++kk) { const float w = wp[(size_t)kk * 3072];
; #pragma unroll
;                 for (int j = 0; j < 9; ++j) a[j] += sil[j * 256 + ks * 32 + kk] * w; }
; #pragma unroll
;             for (int j = 0; j < 9; ++j) red[(ks * 9 + j) * 64 + n] = a[j];
;             __syncthreads();
;             for (int i = tid; i < 576; i += NTHR) { const int j = i >> 6, nn = i & 63; float s = 0.f;
; #pragma unroll
;                 for (int k2 = 0; k2 < 8; ++k2) s += red[(k2 * 9 + j) * 64 + nn];
;                 modp[(kq * 9 + j) * 3072 + cc * 64 + nn] = s; }
;             __syncthreads();
;         } else {
;             int t = it - 192; const float* W; bf16_t* WT; int N; bool isin;
;             if (t < 1024) { W = p.w_in; WT = (bf16_t*)(p.ws + WS_WIN); N = 4096; isin = true; } else { t -= 1024; W = p.w_out; WT = (bf16_t*)(p.ws + WS_WOUT); N = 1024; isin = false; }
;             const int kt = t & 15, nt = t >> 4;
;             const int n = tid & 63, k0 = tid >> 6;
;             const int ncol = nt * 64 + n; int src = ncol;
;             if (isin && ncol < 2048) { const int pnn = ncol >> 8, cc = ncol & 255; const int type = ((cc >> 7) << 1) | ((cc >> 2) & 1); src = type * 512 + 64 * pnn + 16 * ((cc >> 5) & 3) + 4 * ((cc >> 3) & 3) + (cc & 3); }
;             else if (isin && ncol >= 2560 && ncol < 3584) { const int mm = ncol - 2560, g = mm >> 3, i = mm & 7; src = (i < 4) ? 2560 + 4 * g + i : 3072 + 4 * g + (i - 4); }
; #pragma unroll
;             for (int ps = 0; ps < 8; ++ps) { const int k = ps * 8 + k0; fl[k * 65 + n] = W[(size_t)(kt * 64 + k) * N + src]; }
.LBB0_10:
	s_cmpk_gt_i32 s31, 0xbf
	s_mov_b64 s[18:19], -1
	s_cbranch_scc0 .LBB0_22
	s_load_dword s14, s[16:17], 0x0
	s_waitcnt lgkmcnt(0)
	s_cmp_eq_u32 s14, 0x100
	s_cbranch_scc1 .Lp0c_start
	s_cmpk_lt_u32 s31, 0x4c0
	s_cselect_b64 s[20:21], -1, 0
	s_and_b64 s[18:19], s[20:21], exec
	s_cselect_b32 s14, s3, 0xfffffb40
	s_add_i32 s14, s31, s14
	s_lshl_b32 s18, s14, 2
	s_and_b32 s34, s18, 0x7fffffc0
	s_cmpk_lt_u32 s14, 0x200
	s_cselect_b64 s[18:19], -1, 0
	s_and_b64 s[18:19], s[20:21], s[18:19]
	v_or_b32_e32 v2, s34, v26
	s_andn2_b64 vcc, exec, s[18:19]
	s_mov_b64 s[18:19], -1
	s_cbranch_vccz .LBB0_19
	s_add_i32 s18, s14, 0xfffffd80
	s_cmpk_lt_u32 s18, 0x100
	s_cselect_b64 s[18:19], -1, 0
	s_and_b64 s[18:19], s[20:21], s[18:19]
	s_andn2_b64 vcc, exec, s[18:19]
	v_mov_b32_e32 v28, v2
	s_cbranch_vccnz .LBB0_18
	v_add_u32_e32 v3, 0xfffff600, v2
	v_ashrrev_i32_e32 v3, 1, v3
	v_and_b32_e32 v3, -4, v3
	s_and_saveexec_b64 s[18:19], s[6:7]
	s_xor_b64 s[18:19], exec, s[18:19]
	v_add_u32_e32 v28, v27, v3
	s_andn2_saveexec_b64 s[18:19], s[18:19]
	v_add_u32_e32 v28, v44, v3
	s_or_b64 exec, exec, s[18:19]

; __device__ void phase0(LAS unsigned char* lds, const Params& p, int it_lo, int it_hi) {
;     ...
;             int t = it - 192; const float* W; bf16_t* WT; int N; bool isin;
;             if (t < 1024) { W = p.w_in; WT = (bf16_t*)(p.ws + WS_WIN); N = 4096; isin = true; } else { t -= 1024; W = p.w_out; WT = (bf16_t*)(p.ws + WS_WOUT); N = 1024; isin = false; }
;             const int kt = t & 15, nt = t >> 4;
;             const int n = tid & 63, k0 = tid >> 6;
;             const int ncol = nt * 64 + n; int src = ncol;
;             if (isin && ncol < 2048) { const int pnn = ncol >> 8, cc = ncol & 255; const int type = ((cc >> 7) << 1) | ((cc >> 2) & 1); src = type * 512 + 64 * pnn + 16 * ((cc >> 5) & 3) + 4 * ((cc >> 3) & 3) + (cc & 3); }
;             else if (isin && ncol >= 2560 && ncol < 3584) { const int mm = ncol - 2560, g = mm >> 3, i = mm & 7; src = (i < 4) ? 2560 + 4 * g + i : 3072 + 4 * g + (i - 4); }
.Lp0c_start:
	s_cmpk_lt_u32 s31, 0x4c0
	s_cselect_b64 s[20:21], -1, 0
	s_and_b64 s[18:19], s[20:21], exec
	s_cselect_b32 s14, s3, 0xfffffb40
	s_add_i32 s14, s31, s14
	s_lshl_b32 s18, s14, 2
	s_and_b32 s34, s18, 0x7fffffc0
	s_cmpk_lt_u32 s14, 0x200
	s_cselect_b64 s[18:19], -1, 0
	s_and_b64 s[18:19], s[20:21], s[18:19]
	v_or_b32_e32 v2, s34, v26
	s_andn2_b64 vcc, exec, s[18:19]
	s_mov_b64 s[18:19], -1
	s_cbranch_vccz .Lp0c0_19
	s_add_i32 s18, s14, 0xfffffd80
	s_cmpk_lt_u32 s18, 0x100
	s_cselect_b64 s[18:19], -1, 0
	s_and_b64 s[18:19], s[20:21], s[18:19]
	s_andn2_b64 vcc, exec, s[18:19]
	v_mov_b32_e32 v28, v2
	s_cbranch_vccnz .Lp0c0_18
	v_add_u32_e32 v3, 0xfffff600, v2
	v_ashrrev_i32_e32 v3, 1, v3
	v_and_b32_e32 v3, -4, v3
	s_and_saveexec_b64 s[18:19], s[6:7]
	s_xor_b64 s[18:19], exec, s[18:19]
	v_add_u32_e32 v28, v27, v3
	s_andn2_saveexec_b64 s[18:19], s[18:19]
	v_add_u32_e32 v28, v44, v3
	s_or_b64 exec, exec, s[18:19]

; __device__ void phase0(LAS unsigned char* lds, const Params& p, int it_lo, int it_hi) {
;     ...
;             int t = it - 192; const float* W; bf16_t* WT; int N; bool isin;
;             if (t < 1024) { W = p.w_in; WT = (bf16_t*)(p.ws + WS_WIN); N = 4096; isin = true; } else { t -= 1024; W = p.w_out; WT = (bf16_t*)(p.ws + WS_WOUT); N = 1024; isin = false; }
;             const int kt = t & 15, nt = t >> 4;
;             const int n = tid & 63, k0 = tid >> 6;
;             const int ncol = nt * 64 + n; int src = ncol;
;             if (isin && ncol < 2048) { const int pnn = ncol >> 8, cc = ncol & 255; const int type = ((cc >> 7) << 1) | ((cc >> 2) & 1); src = type * 512 + 64 * pnn + 16 * ((cc >> 5) & 3) + 4 * ((cc >> 3) & 3) + (cc & 3); }
;             else if (isin && ncol >= 2560 && ncol < 3584) { const int mm = ncol - 2560, g = mm >> 3, i = mm & 7; src = (i < 4) ? 2560 + 4 * g + i : 3072 + 4 * g + (i - 4); }
; #pragma unroll
;             for (int ps = 0; ps < 8; ++ps) { const int k = ps * 8 + k0; fl[k * 65 + n] = W[(size_t)(kt * 64 + k) * N + src]; }
;     ...
;             *(u32x4*)(WT + (size_t)(nt * 64 + nn) * 1024 + kt * 64 + k8 * 8) = o;
.Lp0c0_21:
	s_and_b64 s[18:19], s[20:21], exec
	s_cselect_b32 s18, 0, 0x800000
	s_add_u32 s18, s70, s18
	s_addc_u32 s19, s71, 0
	s_and_b64 s[76:77], s[20:21], exec
	s_waitcnt lgkmcnt(0)
	s_cselect_b32 s35, s51, s65
	s_cselect_b32 s76, s50, s64
	s_lshl_b32 s14, s14, 6
	s_and_b32 s14, s14, 0x3c0
	v_mov_b32_e32 v2, s76
	v_mov_b32_e32 v3, s35
	s_and_b64 s[20:21], s[20:21], exec
	v_lshl_add_u64 v[2:3], v[28:29], 2, v[2:3]
	v_or_b32_e32 v28, s14, v1
	s_cselect_b32 s20, 12, 10
	v_lshlrev_b64 v[4:5], s20, v[28:29]
	v_or_b32_e32 v28, s14, v50
	v_lshlrev_b64 v[6:7], s20, v[28:29]
	v_or_b32_e32 v28, s14, v51
	v_lshlrev_b64 v[8:9], s20, v[28:29]
	v_or_b32_e32 v28, s14, v52
	v_lshlrev_b64 v[10:11], s20, v[28:29]
	v_or_b32_e32 v28, s14, v53
	v_lshlrev_b64 v[12:13], s20, v[28:29]
	v_or_b32_e32 v28, s14, v54
	v_lshlrev_b64 v[14:15], s20, v[28:29]
	v_or_b32_e32 v28, s14, v55
	v_lshlrev_b64 v[16:17], s20, v[28:29]
	v_or_b32_e32 v28, s14, v56
	v_lshl_add_u64 v[4:5], v[4:5], 2, v[2:3]
	v_lshl_add_u64 v[6:7], v[6:7], 2, v[2:3]
	v_lshl_add_u64 v[8:9], v[8:9], 2, v[2:3]
	v_lshl_add_u64 v[10:11], v[10:11], 2, v[2:3]
	v_lshlrev_b64 v[18:19], s20, v[28:29]
	v_lshl_add_u64 v[12:13], v[12:13], 2, v[2:3]
	v_lshl_add_u64 v[14:15], v[14:15], 2, v[2:3]
	v_lshl_add_u64 v[16:17], v[16:17], 2, v[2:3]
	v_lshl_add_u64 v[2:3], v[18:19], 2, v[2:3]
	global_load_dword v100, v[4:5], off
	s_nop 0
	global_load_dword v101, v[6:7], off
	s_nop 0
	global_load_dword v102, v[8:9], off
	global_load_dword v103, v[10:11], off
	s_nop 0
	global_load_dword v104, v[12:13], off
	global_load_dword v105, v[14:15], off
	global_load_dword v106, v[16:17], off
	global_load_dword v107, v[2:3], off
	v_add_u32_e32 v28, s34, v47
	v_lshlrev_b64 v[2:3], 11, v[28:29]
	s_lshl_b32 s14, s14, 1
	v_lshl_add_u64 v[2:3], s[18:19], 0, v[2:3]
	v_mov_b32_e32 v31, v29
	v_lshl_add_u64 v[2:3], v[2:3], 0, s[14:15]
	v_lshl_add_u64 v[108:109], v[2:3], 0, v[30:31]
	s_mov_b64 s[18:19], 0
	s_add_i32 s31, s31, 0x100
	s_cmpk_lt_u32 s31, 0x4c0
	s_cselect_b64 s[20:21], -1, 0
	s_and_b64 s[18:19], s[20:21], exec
	s_cselect_b32 s14, s3, 0xfffffb40
	s_add_i32 s14, s31, s14
	s_lshl_b32 s18, s14, 2
	s_and_b32 s34, s18, 0x7fffffc0
	s_cmpk_lt_u32 s14, 0x200
	s_cselect_b64 s[18:19], -1, 0
	s_and_b64 s[18:19], s[20:21], s[18:19]
	v_or_b32_e32 v2, s34, v26
	s_andn2_b64 vcc, exec, s[18:19]
	s_mov_b64 s[18:19], -1
	s_cbranch_vccz .Lp0c1_19
	s_add_i32 s18, s14, 0xfffffd80
	s_cmpk_lt_u32 s18, 0x100
	s_cselect_b64 s[18:19], -1, 0
	s_and_b64 s[18:19], s[20:21], s[18:19]
	s_andn2_b64 vcc, exec, s[18:19]
	v_mov_b32_e32 v28, v2
	s_cbranch_vccnz .Lp0c1_18
	v_add_u32_e32 v3, 0xfffff600, v2
	v_ashrrev_i32_e32 v3, 1, v3
	v_and_b32_e32 v3, -4, v3
	s_and_saveexec_b64 s[18:19], s[6:7]
	s_xor_b64 s[18:19], exec, s[18:19]
	v_add_u32_e32 v28, v27, v3
	s_andn2_saveexec_b64 s[18:19], s[18:19]
	v_add_u32_e32 v28, v44, v3
	s_or_b64 exec, exec, s[18:19]

; __device__ void phase0(LAS unsigned char* lds, const Params& p, int it_lo, int it_hi) {
;     ...
;             int t = it - 192; const float* W; bf16_t* WT; int N; bool isin;
;             if (t < 1024) { W = p.w_in; WT = (bf16_t*)(p.ws + WS_WIN); N = 4096; isin = true; } else { t -= 1024; W = p.w_out; WT = (bf16_t*)(p.ws + WS_WOUT); N = 1024; isin = false; }
;             const int kt = t & 15, nt = t >> 4;
;             const int n = tid & 63, k0 = tid >> 6;
;             const int ncol = nt * 64 + n; int src = ncol;
;             if (isin && ncol < 2048) { const int pnn = ncol >> 8, cc = ncol & 255; const int type = ((cc >> 7) << 1) | ((cc >> 2) & 1); src = type * 512 + 64 * pnn + 16 * ((cc >> 5) & 3) + 4 * ((cc >> 3) & 3) + (cc & 3); }
;             else if (isin && ncol >= 2560 && ncol < 3584) { const int mm = ncol - 2560, g = mm >> 3, i = mm & 7; src = (i < 4) ? 2560 + 4 * g + i : 3072 + 4 * g + (i - 4); }
; #pragma unroll
;             for (int ps = 0; ps < 8; ++ps) { const int k = ps * 8 + k0; fl[k * 65 + n] = W[(size_t)(kt * 64 + k) * N + src]; }
;     ...
;             *(u32x4*)(WT + (size_t)(nt * 64 + nn) * 1024 + kt * 64 + k8 * 8) = o;
.Lp0c1_21:
	s_and_b64 s[18:19], s[20:21], exec
	s_cselect_b32 s18, 0, 0x800000
	s_add_u32 s18, s70, s18
	s_addc_u32 s19, s71, 0
	s_and_b64 s[76:77], s[20:21], exec
	s_waitcnt lgkmcnt(0)
	s_cselect_b32 s35, s51, s65
	s_cselect_b32 s76, s50, s64
	s_lshl_b32 s14, s14, 6
	s_and_b32 s14, s14, 0x3c0
	v_mov_b32_e32 v2, s76
	v_mov_b32_e32 v3, s35
	s_and_b64 s[20:21], s[20:21], exec
	v_lshl_add_u64 v[2:3], v[28:29], 2, v[2:3]
	v_or_b32_e32 v28, s14, v1
	s_cselect_b32 s20, 12, 10
	v_lshlrev_b64 v[4:5], s20, v[28:29]
	v_or_b32_e32 v28, s14, v50
	v_lshlrev_b64 v[6:7], s20, v[28:29]
	v_or_b32_e32 v28, s14, v51
	v_lshlrev_b64 v[8:9], s20, v[28:29]
	v_or_b32_e32 v28, s14, v52
	v_lshlrev_b64 v[10:11], s20, v[28:29]
	v_or_b32_e32 v28, s14, v53
	v_lshlrev_b64 v[12:13], s20, v[28:29]
	v_or_b32_e32 v28, s14, v54
	v_lshlrev_b64 v[14:15], s20, v[28:29]
	v_or_b32_e32 v28, s14, v55
	v_lshlrev_b64 v[16:17], s20, v[28:29]
	v_or_b32_e32 v28, s14, v56
	v_lshl_add_u64 v[4:5], v[4:5], 2, v[2:3]
	v_lshl_add_u64 v[6:7], v[6:7], 2, v[2:3]
	v_lshl_add_u64 v[8:9], v[8:9], 2, v[2:3]
	v_lshl_add_u64 v[10:11], v[10:11], 2, v[2:3]
	v_lshlrev_b64 v[18:19], s20, v[28:29]
	v_lshl_add_u64 v[12:13], v[12:13], 2, v[2:3]
	v_lshl_add_u64 v[14:15], v[14:15], 2, v[2:3]
	v_lshl_add_u64 v[16:17], v[16:17], 2, v[2:3]
	v_lshl_add_u64 v[2:3], v[18:19], 2, v[2:3]
	global_load_dword v110, v[4:5], off
	s_nop 0
	global_load_dword v111, v[6:7], off
	s_nop 0
	global_load_dword v112, v[8:9], off
	global_load_dword v113, v[10:11], off
	s_nop 0
	global_load_dword v114, v[12:13], off
	global_load_dword v115, v[14:15], off
	global_load_dword v116, v[16:17], off
	global_load_dword v117, v[2:3], off
	v_add_u32_e32 v28, s34, v47
	v_lshlrev_b64 v[2:3], 11, v[28:29]
	s_lshl_b32 s14, s14, 1
	v_lshl_add_u64 v[2:3], s[18:19], 0, v[2:3]
	v_mov_b32_e32 v31, v29
	v_lshl_add_u64 v[2:3], v[2:3], 0, s[14:15]
	v_lshl_add_u64 v[118:119], v[2:3], 0, v[30:31]
	s_mov_b64 s[18:19], 0
	s_add_i32 s31, s31, 0x100
	s_cmpk_lt_u32 s31, 0x4c0
	s_cselect_b64 s[20:21], -1, 0
	s_and_b64 s[18:19], s[20:21], exec
	s_cselect_b32 s14, s3, 0xfffffb40
	s_add_i32 s14, s31, s14
	s_lshl_b32 s18, s14, 2
	s_and_b32 s34, s18, 0x7fffffc0
	s_cmpk_lt_u32 s14, 0x200
	s_cselect_b64 s[18:19], -1, 0
	s_and_b64 s[18:19], s[20:21], s[18:19]
	v_or_b32_e32 v2, s34, v26
	s_andn2_b64 vcc, exec, s[18:19]
	s_mov_b64 s[18:19], -1
	s_cbranch_vccz .Lp0c2_19
	s_add_i32 s18, s14, 0xfffffd80
	s_cmpk_lt_u32 s18, 0x100
	s_cselect_b64 s[18:19], -1, 0
	s_and_b64 s[18:19], s[20:21], s[18:19]
	s_andn2_b64 vcc, exec, s[18:19]
	v_mov_b32_e32 v28, v2
	s_cbranch_vccnz .Lp0c2_18
	v_add_u32_e32 v3, 0xfffff600, v2
	v_ashrrev_i32_e32 v3, 1, v3
	v_and_b32_e32 v3, -4, v3
	s_and_saveexec_b64 s[18:19], s[6:7]
	s_xor_b64 s[18:19], exec, s[18:19]
	v_add_u32_e32 v28, v27, v3
	s_andn2_saveexec_b64 s[18:19], s[18:19]
	v_add_u32_e32 v28, v44, v3
	s_or_b64 exec, exec, s[18:19]

; __device__ void phase0(LAS unsigned char* lds, const Params& p, int it_lo, int it_hi) {
;     ...
;             int t = it - 192; const float* W; bf16_t* WT; int N; bool isin;
;             if (t < 1024) { W = p.w_in; WT = (bf16_t*)(p.ws + WS_WIN); N = 4096; isin = true; } else { t -= 1024; W = p.w_out; WT = (bf16_t*)(p.ws + WS_WOUT); N = 1024; isin = false; }
;             const int kt = t & 15, nt = t >> 4;
;             const int n = tid & 63, k0 = tid >> 6;
;             const int ncol = nt * 64 + n; int src = ncol;
;             if (isin && ncol < 2048) { const int pnn = ncol >> 8, cc = ncol & 255; const int type = ((cc >> 7) << 1) | ((cc >> 2) & 1); src = type * 512 + 64 * pnn + 16 * ((cc >> 5) & 3) + 4 * ((cc >> 3) & 3) + (cc & 3); }
;             else if (isin && ncol >= 2560 && ncol < 3584) { const int mm = ncol - 2560, g = mm >> 3, i = mm & 7; src = (i < 4) ? 2560 + 4 * g + i : 3072 + 4 * g + (i - 4); }
; #pragma unroll
;             for (int ps = 0; ps < 8; ++ps) { const int k = ps * 8 + k0; fl[k * 65 + n] = W[(size_t)(kt * 64 + k) * N + src]; }
;     ...
;             *(u32x4*)(WT + (size_t)(nt * 64 + nn) * 1024 + kt * 64 + k8 * 8) = o;
.Lp0c2_21:
	s_and_b64 s[18:19], s[20:21], exec
	s_cselect_b32 s18, 0, 0x800000
	s_add_u32 s18, s70, s18
	s_addc_u32 s19, s71, 0
	s_and_b64 s[76:77], s[20:21], exec
	s_waitcnt lgkmcnt(0)
	s_cselect_b32 s35, s51, s65
	s_cselect_b32 s76, s50, s64
	s_lshl_b32 s14, s14, 6
	s_and_b32 s14, s14, 0x3c0
	v_mov_b32_e32 v2, s76
	v_mov_b32_e32 v3, s35
	s_and_b64 s[20:21], s[20:21], exec
	v_lshl_add_u64 v[2:3], v[28:29], 2, v[2:3]
	v_or_b32_e32 v28, s14, v1
	s_cselect_b32 s20, 12, 10
	v_lshlrev_b64 v[4:5], s20, v[28:29]
	v_or_b32_e32 v28, s14, v50
	v_lshlrev_b64 v[6:7], s20, v[28:29]
	v_or_b32_e32 v28, s14, v51
	v_lshlrev_b64 v[8:9], s20, v[28:29]
	v_or_b32_e32 v28, s14, v52
	v_lshlrev_b64 v[10:11], s20, v[28:29]
	v_or_b32_e32 v28, s14, v53
	v_lshlrev_b64 v[12:13], s20, v[28:29]
	v_or_b32_e32 v28, s14, v54
	v_lshlrev_b64 v[14:15], s20, v[28:29]
	v_or_b32_e32 v28, s14, v55
	v_lshlrev_b64 v[16:17], s20, v[28:29]
	v_or_b32_e32 v28, s14, v56
	v_lshl_add_u64 v[4:5], v[4:5], 2, v[2:3]
	v_lshl_add_u64 v[6:7], v[6:7], 2, v[2:3]
	v_lshl_add_u64 v[8:9], v[8:9], 2, v[2:3]
	v_lshl_add_u64 v[10:11], v[10:11], 2, v[2:3]
	v_lshlrev_b64 v[18:19], s20, v[28:29]
	v_lshl_add_u64 v[12:13], v[12:13], 2, v[2:3]
	v_lshl_add_u64 v[14:15], v[14:15], 2, v[2:3]
	v_lshl_add_u64 v[16:17], v[16:17], 2, v[2:3]
	v_lshl_add_u64 v[2:3], v[18:19], 2, v[2:3]
	global_load_dword v120, v[4:5], off
	s_nop 0
	global_load_dword v121, v[6:7], off
	s_nop 0
	global_load_dword v122, v[8:9], off
	global_load_dword v123, v[10:11], off
	s_nop 0
	global_load_dword v124, v[12:13], off
	global_load_dword v125, v[14:15], off
	global_load_dword v126, v[16:17], off
	global_load_dword v127, v[2:3], off
	v_add_u32_e32 v28, s34, v47
	v_lshlrev_b64 v[2:3], 11, v[28:29]
	s_lshl_b32 s14, s14, 1
	v_lshl_add_u64 v[2:3], s[18:19], 0, v[2:3]
	v_mov_b32_e32 v31, v29
	v_lshl_add_u64 v[2:3], v[2:3], 0, s[14:15]
	v_lshl_add_u64 v[128:129], v[2:3], 0, v[30:31]
	s_mov_b64 s[18:19], 0
	s_add_i32 s31, s31, 0x100
	s_cmpk_lt_u32 s31, 0x4c0
	s_cselect_b64 s[20:21], -1, 0
	s_and_b64 s[18:19], s[20:21], exec
	s_cselect_b32 s14, s3, 0xfffffb40
	s_add_i32 s14, s31, s14
	s_lshl_b32 s18, s14, 2
	s_and_b32 s34, s18, 0x7fffffc0
	s_cmpk_lt_u32 s14, 0x200
	s_cselect_b64 s[18:19], -1, 0
	s_and_b64 s[18:19], s[20:21], s[18:19]
	v_or_b32_e32 v2, s34, v26
	s_andn2_b64 vcc, exec, s[18:19]
	s_mov_b64 s[18:19], -1
	s_cbranch_vccz .Lp0c3_19
	s_add_i32 s18, s14, 0xfffffd80
	s_cmpk_lt_u32 s18, 0x100
	s_cselect_b64 s[18:19], -1, 0
	s_and_b64 s[18:19], s[20:21], s[18:19]
	s_andn2_b64 vcc, exec, s[18:19]
	v_mov_b32_e32 v28, v2
	s_cbranch_vccnz .Lp0c3_18
	v_add_u32_e32 v3, 0xfffff600, v2
	v_ashrrev_i32_e32 v3, 1, v3
	v_and_b32_e32 v3, -4, v3
	s_and_saveexec_b64 s[18:19], s[6:7]
	s_xor_b64 s[18:19], exec, s[18:19]
	v_add_u32_e32 v28, v27, v3
	s_andn2_saveexec_b64 s[18:19], s[18:19]
	v_add_u32_e32 v28, v44, v3
	s_or_b64 exec, exec, s[18:19]

; __device__ void phase0(LAS unsigned char* lds, const Params& p, int it_lo, int it_hi) {
;     ...
;             int t = it - 192; const float* W; bf16_t* WT; int N; bool isin;
;             if (t < 1024) { W = p.w_in; WT = (bf16_t*)(p.ws + WS_WIN); N = 4096; isin = true; } else { t -= 1024; W = p.w_out; WT = (bf16_t*)(p.ws + WS_WOUT); N = 1024; isin = false; }
;             const int kt = t & 15, nt = t >> 4;
;             const int n = tid & 63, k0 = tid >> 6;
;             const int ncol = nt * 64 + n; int src = ncol;
;             if (isin && ncol < 2048) { const int pnn = ncol >> 8, cc = ncol & 255; const int type = ((cc >> 7) << 1) | ((cc >> 2) & 1); src = type * 512 + 64 * pnn + 16 * ((cc >> 5) & 3) + 4 * ((cc >> 3) & 3) + (cc & 3); }
;             else if (isin && ncol >= 2560 && ncol < 3584) { const int mm = ncol - 2560, g = mm >> 3, i = mm & 7; src = (i < 4) ? 2560 + 4 * g + i : 3072 + 4 * g + (i - 4); }
; #pragma unroll
;             for (int ps = 0; ps < 8; ++ps) { const int k = ps * 8 + k0; fl[k * 65 + n] = W[(size_t)(kt * 64 + k) * N + src]; }
;     ...
;             *(u32x4*)(WT + (size_t)(nt * 64 + nn) * 1024 + kt * 64 + k8 * 8) = o;
.Lp0c3_21:
	s_and_b64 s[18:19], s[20:21], exec
	s_cselect_b32 s18, 0, 0x800000
	s_add_u32 s18, s70, s18
	s_addc_u32 s19, s71, 0
	s_and_b64 s[76:77], s[20:21], exec
	s_waitcnt lgkmcnt(0)
	s_cselect_b32 s35, s51, s65
	s_cselect_b32 s76, s50, s64
	s_lshl_b32 s14, s14, 6
	s_and_b32 s14, s14, 0x3c0
	v_mov_b32_e32 v2, s76
	v_mov_b32_e32 v3, s35
	s_and_b64 s[20:21], s[20:21], exec
	v_lshl_add_u64 v[2:3], v[28:29], 2, v[2:3]
	v_or_b32_e32 v28, s14, v1
	s_cselect_b32 s20, 12, 10
	v_lshlrev_b64 v[4:5], s20, v[28:29]
	v_or_b32_e32 v28, s14, v50
	v_lshlrev_b64 v[6:7], s20, v[28:29]
	v_or_b32_e32 v28, s14, v51
	v_lshlrev_b64 v[8:9], s20, v[28:29]
	v_or_b32_e32 v28, s14, v52
	v_lshlrev_b64 v[10:11], s20, v[28:29]
	v_or_b32_e32 v28, s14, v53
	v_lshlrev_b64 v[12:13], s20, v[28:29]
	v_or_b32_e32 v28, s14, v54
	v_lshlrev_b64 v[14:15], s20, v[28:29]
	v_or_b32_e32 v28, s14, v55
	v_lshlrev_b64 v[16:17], s20, v[28:29]
	v_or_b32_e32 v28, s14, v56
	v_lshl_add_u64 v[4:5], v[4:5], 2, v[2:3]
	v_lshl_add_u64 v[6:7], v[6:7], 2, v[2:3]
	v_lshl_add_u64 v[8:9], v[8:9], 2, v[2:3]
	v_lshl_add_u64 v[10:11], v[10:11], 2, v[2:3]
	v_lshlrev_b64 v[18:19], s20, v[28:29]
	v_lshl_add_u64 v[12:13], v[12:13], 2, v[2:3]
	v_lshl_add_u64 v[14:15], v[14:15], 2, v[2:3]
	v_lshl_add_u64 v[16:17], v[16:17], 2, v[2:3]
	v_lshl_add_u64 v[2:3], v[18:19], 2, v[2:3]
	global_load_dword v130, v[4:5], off
	s_nop 0
	global_load_dword v131, v[6:7], off
	s_nop 0
	global_load_dword v132, v[8:9], off
	global_load_dword v133, v[10:11], off
	s_nop 0
	global_load_dword v134, v[12:13], off
	global_load_dword v135, v[14:15], off
	global_load_dword v136, v[16:17], off
	global_load_dword v137, v[2:3], off
	v_add_u32_e32 v28, s34, v47
	v_lshlrev_b64 v[2:3], 11, v[28:29]
	s_lshl_b32 s14, s14, 1
	v_lshl_add_u64 v[2:3], s[18:19], 0, v[2:3]
	v_mov_b32_e32 v31, v29
	v_lshl_add_u64 v[2:3], v[2:3], 0, s[14:15]
	v_lshl_add_u64 v[138:139], v[2:3], 0, v[30:31]
	s_mov_b64 s[18:19], 0
	s_add_i32 s31, s31, 0x100
	s_cmpk_lt_u32 s31, 0x4c0
	s_cselect_b64 s[20:21], -1, 0
	s_and_b64 s[18:19], s[20:21], exec
	s_cselect_b32 s14, s3, 0xfffffb40
	s_add_i32 s14, s31, s14
	s_lshl_b32 s18, s14, 2
	s_and_b32 s34, s18, 0x7fffffc0
	s_cmpk_lt_u32 s14, 0x200
	s_cselect_b64 s[18:19], -1, 0
	s_and_b64 s[18:19], s[20:21], s[18:19]
	v_or_b32_e32 v2, s34, v26
	s_andn2_b64 vcc, exec, s[18:19]
	s_mov_b64 s[18:19], -1
	s_cbranch_vccz .Lp0c4_19
	s_add_i32 s18, s14, 0xfffffd80
	s_cmpk_lt_u32 s18, 0x100
	s_cselect_b64 s[18:19], -1, 0
	s_and_b64 s[18:19], s[20:21], s[18:19]
	s_andn2_b64 vcc, exec, s[18:19]
	v_mov_b32_e32 v28, v2
	s_cbranch_vccnz .Lp0c4_18
	v_add_u32_e32 v3, 0xfffff600, v2
	v_ashrrev_i32_e32 v3, 1, v3
	v_and_b32_e32 v3, -4, v3
	s_and_saveexec_b64 s[18:19], s[6:7]
	s_xor_b64 s[18:19], exec, s[18:19]
	v_add_u32_e32 v28, v27, v3
	s_andn2_saveexec_b64 s[18:19], s[18:19]
	v_add_u32_e32 v28, v44, v3
	s_or_b64 exec, exec, s[18:19]

; __device__ __forceinline__ unsigned cvt_pk_bf16(float lo, float hi) { unsigned r; asm volatile("v_cvt_pk_bf16_f32 %0, %1, %2" : "=v"(r) : "v"(lo), "v"(hi)); return r; }
; __device__ void phase0(LAS unsigned char* lds, const Params& p, int it_lo, int it_hi) {
;     ...
;             for (int ps = 0; ps < 8; ++ps) { const int k = ps * 8 + k0; fl[k * 65 + n] = W[(size_t)(kt * 64 + k) * N + src]; }
;             __syncthreads();
;             const int nn = tid >> 3, k8 = tid & 7;
;             float v[8];
; #pragma unroll
;             for (int j = 0; j < 8; ++j) v[j] = fl[(k8 * 8 + j) * 65 + nn];
;             u32x4 o = {cvt_pk_bf16(v[0], v[1]), cvt_pk_bf16(v[2], v[3]), cvt_pk_bf16(v[4], v[5]), cvt_pk_bf16(v[6], v[7])};
;             *(u32x4*)(WT + (size_t)(nt * 64 + nn) * 1024 + kt * 64 + k8 * 8) = o;
;             __syncthreads();
.Lp0c4_21:
	s_and_b64 s[18:19], s[20:21], exec
	s_cselect_b32 s18, 0, 0x800000
	s_add_u32 s18, s70, s18
	s_addc_u32 s19, s71, 0
	s_and_b64 s[76:77], s[20:21], exec
	s_waitcnt lgkmcnt(0)
	s_cselect_b32 s35, s51, s65
	s_cselect_b32 s76, s50, s64
	s_lshl_b32 s14, s14, 6
	s_and_b32 s14, s14, 0x3c0
	v_mov_b32_e32 v2, s76
	v_mov_b32_e32 v3, s35
	s_and_b64 s[20:21], s[20:21], exec
	v_lshl_add_u64 v[2:3], v[28:29], 2, v[2:3]
	v_or_b32_e32 v28, s14, v1
	s_cselect_b32 s20, 12, 10
	v_lshlrev_b64 v[4:5], s20, v[28:29]
	v_or_b32_e32 v28, s14, v50
	v_lshlrev_b64 v[6:7], s20, v[28:29]
	v_or_b32_e32 v28, s14, v51
	v_lshlrev_b64 v[8:9], s20, v[28:29]
	v_or_b32_e32 v28, s14, v52
	v_lshlrev_b64 v[10:11], s20, v[28:29]
	v_or_b32_e32 v28, s14, v53
	v_lshlrev_b64 v[12:13], s20, v[28:29]
	v_or_b32_e32 v28, s14, v54
	v_lshlrev_b64 v[14:15], s20, v[28:29]
	v_or_b32_e32 v28, s14, v55
	v_lshlrev_b64 v[16:17], s20, v[28:29]
	v_or_b32_e32 v28, s14, v56
	v_lshl_add_u64 v[4:5], v[4:5], 2, v[2:3]
	v_lshl_add_u64 v[6:7], v[6:7], 2, v[2:3]
	v_lshl_add_u64 v[8:9], v[8:9], 2, v[2:3]
	v_lshl_add_u64 v[10:11], v[10:11], 2, v[2:3]
	v_lshlrev_b64 v[18:19], s20, v[28:29]
	v_lshl_add_u64 v[12:13], v[12:13], 2, v[2:3]
	v_lshl_add_u64 v[14:15], v[14:15], 2, v[2:3]
	v_lshl_add_u64 v[16:17], v[16:17], 2, v[2:3]
	v_lshl_add_u64 v[2:3], v[18:19], 2, v[2:3]
	global_load_dword v140, v[4:5], off
	s_nop 0
	global_load_dword v141, v[6:7], off
	s_nop 0
	global_load_dword v142, v[8:9], off
	global_load_dword v143, v[10:11], off
	s_nop 0
	global_load_dword v144, v[12:13], off
	global_load_dword v145, v[14:15], off
	global_load_dword v146, v[16:17], off
	global_load_dword v147, v[2:3], off
	v_add_u32_e32 v28, s34, v47
	v_lshlrev_b64 v[2:3], 11, v[28:29]
	s_lshl_b32 s14, s14, 1
	v_lshl_add_u64 v[2:3], s[18:19], 0, v[2:3]
	v_mov_b32_e32 v31, v29
	v_lshl_add_u64 v[2:3], v[2:3], 0, s[14:15]
	v_lshl_add_u64 v[148:149], v[2:3], 0, v[30:31]
	s_mov_b64 s[18:19], 0
	s_waitcnt vmcnt(39)
	ds_write_b32 v61, v100
	s_waitcnt vmcnt(38)
	ds_write_b32 v61, v101 offset:2080
	s_waitcnt vmcnt(37)
	ds_write_b32 v61, v102 offset:4160
	s_waitcnt vmcnt(36)
	ds_write_b32 v61, v103 offset:6240
	s_waitcnt vmcnt(35)
	ds_write_b32 v61, v104 offset:8320
	s_waitcnt vmcnt(34)
	ds_write_b32 v61, v105 offset:10400
	s_waitcnt vmcnt(33)
	ds_write_b32 v61, v106 offset:12480
	s_waitcnt vmcnt(32)
	ds_write_b32 v61, v107 offset:14560
	s_waitcnt lgkmcnt(0)
	s_barrier
	ds_read2_b32 v[4:5], v62 offset1:65
	ds_read2_b32 v[6:7], v62 offset0:130 offset1:195
	ds_read2_b32 v[8:9], v64 offset0:4 offset1:69
	ds_read2_b32 v[10:11], v64 offset0:134 offset1:199
	s_waitcnt lgkmcnt(3)
	v_cvt_pk_bf16_f32 v2, v4, v5
	s_waitcnt lgkmcnt(2)
	v_cvt_pk_bf16_f32 v3, v6, v7
	s_waitcnt lgkmcnt(1)
	v_cvt_pk_bf16_f32 v4, v8, v9
	s_waitcnt lgkmcnt(0)
	v_cvt_pk_bf16_f32 v5, v10, v11
	s_nop 0
	global_store_dwordx4 v[108:109], v[2:5], off
	s_barrier
	s_waitcnt vmcnt(32)
	ds_write_b32 v61, v110
	s_waitcnt vmcnt(31)
	ds_write_b32 v61, v111 offset:2080
	s_waitcnt vmcnt(30)
	ds_write_b32 v61, v112 offset:4160
	s_waitcnt vmcnt(29)
	ds_write_b32 v61, v113 offset:6240
	s_waitcnt vmcnt(28)
	ds_write_b32 v61, v114 offset:8320
	s_waitcnt vmcnt(27)
	ds_write_b32 v61, v115 offset:10400
	s_waitcnt vmcnt(26)
	ds_write_b32 v61, v116 offset:12480
	s_waitcnt vmcnt(25)
	ds_write_b32 v61, v117 offset:14560
	s_waitcnt lgkmcnt(0)
	s_barrier
	ds_read2_b32 v[4:5], v62 offset1:65
	ds_read2_b32 v[6:7], v62 offset0:130 offset1:195
	ds_read2_b32 v[8:9], v64 offset0:4 offset1:69
	ds_read2_b32 v[10:11], v64 offset0:134 offset1:199
	s_waitcnt lgkmcnt(3)
	v_cvt_pk_bf16_f32 v2, v4, v5
	s_waitcnt lgkmcnt(2)
	v_cvt_pk_bf16_f32 v3, v6, v7
	s_waitcnt lgkmcnt(1)
	v_cvt_pk_bf16_f32 v4, v8, v9
	s_waitcnt lgkmcnt(0)
	v_cvt_pk_bf16_f32 v5, v10, v11
	s_nop 0
	global_store_dwordx4 v[118:119], v[2:5], off
	s_barrier
	s_waitcnt vmcnt(25)
	ds_write_b32 v61, v120
	s_waitcnt vmcnt(24)
	ds_write_b32 v61, v121 offset:2080
	s_waitcnt vmcnt(23)
	ds_write_b32 v61, v122 offset:4160
	s_waitcnt vmcnt(22)
	ds_write_b32 v61, v123 offset:6240
	s_waitcnt vmcnt(21)
	ds_write_b32 v61, v124 offset:8320
	s_waitcnt vmcnt(20)
	ds_write_b32 v61, v125 offset:10400
	s_waitcnt vmcnt(19)
	ds_write_b32 v61, v126 offset:12480
	s_waitcnt vmcnt(18)
	ds_write_b32 v61, v127 offset:14560
	s_waitcnt lgkmcnt(0)
	s_barrier
	ds_read2_b32 v[4:5], v62 offset1:65
	ds_read2_b32 v[6:7], v62 offset0:130 offset1:195
	ds_read2_b32 v[8:9], v64 offset0:4 offset1:69
	ds_read2_b32 v[10:11], v64 offset0:134 offset1:199
	s_waitcnt lgkmcnt(3)
	v_cvt_pk_bf16_f32 v2, v4, v5
	s_waitcnt lgkmcnt(2)
	v_cvt_pk_bf16_f32 v3, v6, v7
	s_waitcnt lgkmcnt(1)
	v_cvt_pk_bf16_f32 v4, v8, v9
	s_waitcnt lgkmcnt(0)
	v_cvt_pk_bf16_f32 v5, v10, v11
	s_nop 0
	global_store_dwordx4 v[128:129], v[2:5], off
	s_barrier
	s_waitcnt vmcnt(18)
	ds_write_b32 v61, v130
	s_waitcnt vmcnt(17)
	ds_write_b32 v61, v131 offset:2080
	s_waitcnt vmcnt(16)
	ds_write_b32 v61, v132 offset:4160
	s_waitcnt vmcnt(15)
	ds_write_b32 v61, v133 offset:6240
	s_waitcnt vmcnt(14)
	ds_write_b32 v61, v134 offset:8320
	s_waitcnt vmcnt(13)
	ds_write_b32 v61, v135 offset:10400
	s_waitcnt vmcnt(12)
	ds_write_b32 v61, v136 offset:12480
	s_waitcnt vmcnt(11)
	ds_write_b32 v61, v137 offset:14560
	s_waitcnt lgkmcnt(0)
	s_barrier
	ds_read2_b32 v[4:5], v62 offset1:65
	ds_read2_b32 v[6:7], v62 offset0:130 offset1:195
	ds_read2_b32 v[8:9], v64 offset0:4 offset1:69
	ds_read2_b32 v[10:11], v64 offset0:134 offset1:199
	s_waitcnt lgkmcnt(3)
	v_cvt_pk_bf16_f32 v2, v4, v5
	s_waitcnt lgkmcnt(2)
	v_cvt_pk_bf16_f32 v3, v6, v7
	s_waitcnt lgkmcnt(1)
	v_cvt_pk_bf16_f32 v4, v8, v9
	s_waitcnt lgkmcnt(0)
	v_cvt_pk_bf16_f32 v5, v10, v11
	s_nop 0
	global_store_dwordx4 v[138:139], v[2:5], off
	s_barrier
	s_waitcnt vmcnt(11)
	ds_write_b32 v61, v140
	s_waitcnt vmcnt(10)
	ds_write_b32 v61, v141 offset:2080
	s_waitcnt vmcnt(9)
	ds_write_b32 v61, v142 offset:4160
	s_waitcnt vmcnt(8)
	ds_write_b32 v61, v143 offset:6240
	s_waitcnt vmcnt(7)
	ds_write_b32 v61, v144 offset:8320
	s_waitcnt vmcnt(6)
	ds_write_b32 v61, v145 offset:10400
	s_waitcnt vmcnt(5)
	ds_write_b32 v61, v146 offset:12480
	s_waitcnt vmcnt(4)
	ds_write_b32 v61, v147 offset:14560
	s_waitcnt lgkmcnt(0)
	s_barrier
	ds_read2_b32 v[4:5], v62 offset1:65
	ds_read2_b32 v[6:7], v62 offset0:130 offset1:195
	ds_read2_b32 v[8:9], v64 offset0:4 offset1:69
	ds_read2_b32 v[10:11], v64 offset0:134 offset1:199
	s_waitcnt lgkmcnt(3)
	v_cvt_pk_bf16_f32 v2, v4, v5
	s_waitcnt lgkmcnt(2)
	v_cvt_pk_bf16_f32 v3, v6, v7
	s_waitcnt lgkmcnt(1)
	v_cvt_pk_bf16_f32 v4, v8, v9
	s_waitcnt lgkmcnt(0)
	v_cvt_pk_bf16_f32 v5, v10, v11
	s_nop 0
	global_store_dwordx4 v[148:149], v[2:5], off
	s_barrier
	s_branch .LBB0_30
